# first PV0 transposed reads issued before the rescale test (rescale temporaries moved to free registers)
# speedup vs baseline: 1.0274x; 1.0019x over previous
; __device__ __forceinline__ void sm_half(f32x16& p, float& m_reg, float& l_reg, float& alpha, bf16x8& paL, bf16x8& paH) {
;   float a = fmaxf(fmaxf(p[0], p[1]), p[2]), b = fmaxf(fmaxf(p[3], p[4]), p[5]);
;   a = fmaxf(fmaxf(a, p[6]), p[7]); b = fmaxf(fmaxf(b, p[8]), p[9]); a = fmaxf(fmaxf(a, p[10]), p[11]); b = fmaxf(fmaxf(b, p[12]), p[13]); a = fmaxf(fmaxf(a, p[14]), p[15]);
;   float pmax = fmaxf(a, b);
;   { auto rr = __builtin_amdgcn_permlane32_swap(__float_as_uint(pmax), __float_as_uint(pmax), false, false);
;     pmax = fmaxf(__uint_as_float(rr[0]), __uint_as_float(rr[1])); }
;   const bool keep = __all(pmax - m_reg <= THRL);
;   const float mn = keep ? m_reg : fmaxf(m_reg, pmax);
;   alpha = __builtin_amdgcn_exp2f(m_reg - mn); m_reg = mn;
; #pragma unroll
;   for (int r = 0; r < 16; ++r) p[r] = __builtin_amdgcn_exp2f(p[r] - mn);
;   float ps = 0;
; #pragma unroll
;   for (int r = 0; r < 16; ++r) ps += p[r];
;   { auto rr = __builtin_amdgcn_permlane32_swap(__float_as_uint(ps), __float_as_uint(ps), false, false);
;     ps = __uint_as_float(rr[0]) + __uint_as_float(rr[1]); }
;   l_reg = l_reg * alpha + ps;
;     ...
;   PK4(p, 0, paL); PK4(p, 8, paH);
;     ...
; }
; template <int H> __device__ __forceinline__ void qkt_half(f32x16& p, const char* Kn, const char* Kr, const bf16x8* qr, int r32, int hi) {
;   p = f32x16{};
; #pragma unroll
;   for (int d0 = 0; d0 < 8; ++d0) { const int cb = (d0 * 16 + hi * 8) * 2;
;     const bf16x8 f = *reinterpret_cast<const bf16x8*>(Kn + KSWZ(32 * H + r32, cb)); p = __builtin_amdgcn_mfma_f32_32x32x16_bf16(f, qr[d0], p, 0, 0, 0); }
; #pragma unroll
;   for (int d0 = 0; d0 < 4; ++d0) { const int cb = (d0 * 16 + hi * 8) * 2;
;     const bf16x8 f = *reinterpret_cast<const bf16x8*>(Kr + KRSWZ(32 * H + r32, cb)); p = __builtin_amdgcn_mfma_f32_32x32x16_bf16(f, qr[8 + d0], p, 0, 0, 0); }
; }
; template <int H, int D0> __device__ __forceinline__ VFrag pv_rd(int vb) {
;   VFrag f; f.l0 = tr_read<v_rd_off(D0, 2 * H, 0)>(vb); f.h0 = tr_read<v_rd_off(D0, 2 * H, 1)>(vb); f.l1 = tr_read<v_rd_off(D0, 2 * H + 1, 0)>(vb); f.h1 = tr_read<v_rd_off(D0, 2 * H + 1, 1)>(vb); return f;
; }
; __device__ __forceinline__ void pv_mma(f32x16& od, VFrag& f, bf16x8 paL, bf16x8 paH) {
;     ...
;   od = __builtin_amdgcn_mfma_f32_32x32x16_bf16(paL, PK(f.l0, f.h0), od, 0, 0, 0);
;   od = __builtin_amdgcn_mfma_f32_32x32x16_bf16(paH, PK(f.l1, f.h1), od, 0, 0, 0);
;     ...
; }
.Lcont_00:
	v_mfma_f32_32x32x16_bf16 v[66:81], v[202:205], v[110:113], v[66:81]
	v_exp_f32_e32 v82, v82
	v_mfma_f32_32x32x16_bf16 v[66:81], v[206:209], v[114:117], v[66:81]
	v_exp_f32_e32 v83, v83
	v_exp_f32_e32 v84, v84
	v_exp_f32_e32 v85, v85
	v_mfma_f32_32x32x16_bf16 v[66:81], v[210:213], v[118:121], v[66:81]
	v_exp_f32_e32 v86, v86
	v_exp_f32_e32 v87, v87
	v_add_f32_e32 v164, v83, v82
	v_exp_f32_e32 v88, v88
	s_waitcnt lgkmcnt(4)
	v_mfma_f32_32x32x16_bf16 v[66:81], v[214:217], v[122:125], v[66:81]
	v_add_f32_e32 v164, v84, v164
	v_exp_f32_e32 v89, v89
	v_add_f32_e32 v164, v85, v164
	v_exp_f32_e32 v90, v90
	v_add_f32_e32 v164, v86, v164
	v_mfma_f32_32x32x16_bf16 v[66:81], v[218:221], v[126:129], v[66:81]
	v_exp_f32_e32 v91, v91
	v_add_f32_e32 v164, v87, v164
	v_exp_f32_e32 v92, v92
	v_add_f32_e32 v164, v88, v164
	s_waitcnt lgkmcnt(0)
	v_mfma_f32_32x32x16_bf16 v[66:81], v[222:225], v[130:133], v[66:81]
	v_exp_f32_e32 v93, v93
	v_add_f32_e32 v164, v89, v164
	v_exp_f32_e32 v94, v94
	v_add_f32_e32 v164, v90, v164
	v_exp_f32_e32 v95, v95
	v_mfma_f32_32x32x16_bf16 v[66:81], v[226:229], v[134:137], v[66:81]
	v_add_f32_e32 v164, v91, v164
	v_exp_f32_e32 v96, v96
	v_add_f32_e32 v164, v92, v164
	v_exp_f32_e32 v97, v97
	v_add_f32_e32 v164, v93, v164
	v_add_f32_e32 v164, v94, v164
	v_mfma_f32_32x32x16_bf16 v[66:81], v[230:233], v[138:141], v[66:81]
	v_add_f32_e32 v164, v95, v164
	v_add_f32_e32 v164, v96, v164
	v_add_f32_e32 v198, v97, v164
	v_cvt_pk_bf16_f32 v82, v82, v83
	v_cvt_pk_bf16_f32 v83, v84, v85
	v_mfma_f32_32x32x16_bf16 v[66:81], v[234:237], v[142:145], v[66:81]
	v_mfma_f32_32x32x16_bf16 v[66:81], v[250:253], v[252:255], v[66:81]
	v_cvt_pk_bf16_f32 v84, v86, v87
	v_cvt_pk_bf16_f32 v85, v88, v89
	v_cvt_pk_bf16_f32 v86, v90, v91
	v_cvt_pk_bf16_f32 v87, v92, v93
	v_cvt_pk_bf16_f32 v88, v94, v95
	v_cvt_pk_bf16_f32 v89, v96, v97
	ds_read_b64_tr_b16 v[90:91], v175 offset:0
	ds_read_b64_tr_b16 v[92:93], v175 offset:0x800
	ds_read_b64_tr_b16 v[94:95], v175 offset:0x1000
	ds_read_b64_tr_b16 v[96:97], v175 offset:0x1800
	ds_read_b64_tr_b16 v[202:203], v175 offset:0x200
	ds_read_b64_tr_b16 v[204:205], v175 offset:0xa00
	ds_read_b64_tr_b16 v[206:207], v175 offset:0x1200
	ds_read_b64_tr_b16 v[208:209], v175 offset:0x1a00
	s_nop 0
	v_permlane32_swap_b32_e32 v82, v84
	v_permlane32_swap_b32_e32 v83, v85
	v_permlane32_swap_b32_e32 v86, v88
	v_permlane32_swap_b32_e32 v87, v89
	s_cbranch_scc1 .LBB0_525
	s_and_saveexec_b64 s[64:65], s[0:1]
	ds_write_b32 v196, v0 offset:128
	s_or_b64 exec, exec, s[64:65]
	s_waitcnt lgkmcnt(0)
	v_add_u32_e32 v164, s80, v176
	ds_read_b128 v[222:225], v164 offset:224
	ds_read_b128 v[226:229], v164 offset:192
	ds_read_b128 v[230:233], v164 offset:160
	ds_read_b128 v[234:237], v164 offset:128
	s_waitcnt lgkmcnt(0)
	v_pk_mul_f32 v[62:63], v[62:63], v[222:223]
	v_pk_mul_f32 v[58:59], v[58:59], v[226:227]
	v_pk_mul_f32 v[54:55], v[54:55], v[230:231]
	v_pk_mul_f32 v[64:65], v[64:65], v[224:225]
	v_pk_mul_f32 v[60:61], v[60:61], v[228:229]
	v_pk_mul_f32 v[56:57], v[56:57], v[232:233]
	v_pk_mul_f32 v[52:53], v[52:53], v[236:237]
	v_pk_mul_f32 v[50:51], v[50:51], v[234:235]
	v_pk_mul_f32 v[46:47], v[46:47], v[222:223]
	v_pk_mul_f32 v[42:43], v[42:43], v[226:227]
	v_pk_mul_f32 v[38:39], v[38:39], v[230:231]
	v_pk_mul_f32 v[48:49], v[48:49], v[224:225]
	v_pk_mul_f32 v[44:45], v[44:45], v[228:229]
	v_pk_mul_f32 v[40:41], v[40:41], v[232:233]
	v_pk_mul_f32 v[36:37], v[36:37], v[236:237]
	v_pk_mul_f32 v[34:35], v[34:35], v[234:235]
	v_pk_mul_f32 v[30:31], v[30:31], v[222:223]
	v_pk_mul_f32 v[26:27], v[26:27], v[226:227]
	v_pk_mul_f32 v[22:23], v[22:23], v[230:231]
	v_pk_mul_f32 v[32:33], v[32:33], v[224:225]
	v_pk_mul_f32 v[28:29], v[28:29], v[228:229]
	v_pk_mul_f32 v[24:25], v[24:25], v[232:233]
	v_pk_mul_f32 v[20:21], v[20:21], v[236:237]
	v_pk_mul_f32 v[18:19], v[18:19], v[234:235]
	v_pk_mul_f32 v[14:15], v[14:15], v[222:223]
	v_pk_mul_f32 v[10:11], v[10:11], v[226:227]
	v_pk_mul_f32 v[6:7], v[6:7], v[230:231]
	v_pk_mul_f32 v[16:17], v[16:17], v[224:225]
	v_pk_mul_f32 v[12:13], v[12:13], v[228:229]
	v_pk_mul_f32 v[8:9], v[8:9], v[232:233]
	v_pk_mul_f32 v[4:5], v[4:5], v[236:237]
	v_pk_mul_f32 v[2:3], v[2:3], v[234:235]
.LBB0_525:
.LBB0_527:
	s_waitcnt lgkmcnt(4)
	v_mfma_f32_32x32x16_bf16 v[50:65], v[82:85], v[90:93], v[50:65]
	ds_read_b64_tr_b16 v[90:91], v175 offset:0x400
	ds_read_b64_tr_b16 v[92:93], v175 offset:0xc00
	ds_read_b64_tr_b16 v[210:211], v175 offset:0x1400
	ds_read_b64_tr_b16 v[212:213], v175 offset:0x1c00
	s_waitcnt lgkmcnt(4)
	ds_read_b64_tr_b16 v[214:215], v175 offset:0x600
	ds_read_b64_tr_b16 v[216:217], v175 offset:0xe00
	v_mfma_f32_32x32x16_bf16 v[50:65], v[86:89], v[94:97], v[50:65]
	ds_read_b64_tr_b16 v[94:95], v175 offset:0x1600
	ds_read_b64_tr_b16 v[96:97], v175 offset:0x1e00
	s_waitcnt lgkmcnt(4)
	s_waitcnt lgkmcnt(0)
	v_mfma_f32_32x32x16_bf16 v[34:49], v[82:85], v[202:205], v[34:49]
	v_max_f32_e32 v201, v66, v67
	v_max3_f32 v202, v69, v70, v71
	v_max3_f32 v201, v201, v68, v72
	v_max3_f32 v202, v202, v74, v75
	v_max3_f32 v201, v201, v73, v76
	v_max3_f32 v202, v202, v78, v79
	v_max3_f32 v201, v201, v77, v80
	v_max3_f32 v201, v201, v81, v202
	v_mov_b32_e32 v202, v201
	s_nop 1
	v_permlane32_swap_b32_e32 v201, v202
	v_mfma_f32_32x32x16_bf16 v[18:33], v[82:85], v[90:93], v[18:33]
	v_max_f32_e32 v90, v201, v202
	v_cmp_ge_f32_e32 vcc, s99, v90
	s_cmp_eq_u64 vcc, exec
	s_cbranch_scc0 .Lrare_01
	v_mov_b32_e32 v200, 1.0

; __device__ __forceinline__ void sm_half(f32x16& p, float& m_reg, float& l_reg, float& alpha, bf16x8& paL, bf16x8& paH) {
;   float a = fmaxf(fmaxf(p[0], p[1]), p[2]), b = fmaxf(fmaxf(p[3], p[4]), p[5]);
;   a = fmaxf(fmaxf(a, p[6]), p[7]); b = fmaxf(fmaxf(b, p[8]), p[9]); a = fmaxf(fmaxf(a, p[10]), p[11]); b = fmaxf(fmaxf(b, p[12]), p[13]); a = fmaxf(fmaxf(a, p[14]), p[15]);
;   float pmax = fmaxf(a, b);
;   { auto rr = __builtin_amdgcn_permlane32_swap(__float_as_uint(pmax), __float_as_uint(pmax), false, false);
;     pmax = fmaxf(__uint_as_float(rr[0]), __uint_as_float(rr[1])); }
;   const bool keep = __all(pmax - m_reg <= THRL);
;   const float mn = keep ? m_reg : fmaxf(m_reg, pmax);
;   alpha = __builtin_amdgcn_exp2f(m_reg - mn); m_reg = mn;
; #pragma unroll
;   for (int r = 0; r < 16; ++r) p[r] = __builtin_amdgcn_exp2f(p[r] - mn);
;   float ps = 0;
; #pragma unroll
;   for (int r = 0; r < 16; ++r) ps += p[r];
;   { auto rr = __builtin_amdgcn_permlane32_swap(__float_as_uint(ps), __float_as_uint(ps), false, false);
;     ps = __uint_as_float(rr[0]) + __uint_as_float(rr[1]); }
;   l_reg = l_reg * alpha + ps;
;     ...
;   PK4(p, 0, paL); PK4(p, 8, paH);
;     ...
; }
; template <int H> __device__ __forceinline__ void qkt_half(f32x16& p, const char* Kn, const char* Kr, const bf16x8* qr, int r32, int hi) {
;   p = f32x16{};
; #pragma unroll
;   for (int d0 = 0; d0 < 8; ++d0) { const int cb = (d0 * 16 + hi * 8) * 2;
;     const bf16x8 f = *reinterpret_cast<const bf16x8*>(Kn + KSWZ(32 * H + r32, cb)); p = __builtin_amdgcn_mfma_f32_32x32x16_bf16(f, qr[d0], p, 0, 0, 0); }
; #pragma unroll
;   for (int d0 = 0; d0 < 4; ++d0) { const int cb = (d0 * 16 + hi * 8) * 2;
;     const bf16x8 f = *reinterpret_cast<const bf16x8*>(Kr + KRSWZ(32 * H + r32, cb)); p = __builtin_amdgcn_mfma_f32_32x32x16_bf16(f, qr[8 + d0], p, 0, 0, 0); }
; }
; template <int H, int D0> __device__ __forceinline__ VFrag pv_rd(int vb) {
;   VFrag f; f.l0 = tr_read<v_rd_off(D0, 2 * H, 0)>(vb); f.h0 = tr_read<v_rd_off(D0, 2 * H, 1)>(vb); f.l1 = tr_read<v_rd_off(D0, 2 * H + 1, 0)>(vb); f.h1 = tr_read<v_rd_off(D0, 2 * H + 1, 1)>(vb); return f;
; }
; __device__ __forceinline__ void pv_mma(f32x16& od, VFrag& f, bf16x8 paL, bf16x8 paH) {
;     ...
;   od = __builtin_amdgcn_mfma_f32_32x32x16_bf16(paL, PK(f.l0, f.h0), od, 0, 0, 0);
;   od = __builtin_amdgcn_mfma_f32_32x32x16_bf16(paH, PK(f.l1, f.h1), od, 0, 0, 0);
;     ...
; }
.Lcont_10:
	v_mfma_f32_32x32x16_bf16 v[66:81], v[212:215], v[110:113], v[66:81]
	v_exp_f32_e32 v82, v82
	v_mfma_f32_32x32x16_bf16 v[66:81], v[216:219], v[114:117], v[66:81]
	v_exp_f32_e32 v83, v83
	v_exp_f32_e32 v84, v84
	v_mfma_f32_32x32x16_bf16 v[66:81], v[220:223], v[118:121], v[66:81]
	v_exp_f32_e32 v85, v85
	v_exp_f32_e32 v86, v86
	v_exp_f32_e32 v163, v90
	v_exp_f32_e32 v166, v91
	s_waitcnt lgkmcnt(4)
	v_mfma_f32_32x32x16_bf16 v[66:81], v[224:227], v[122:125], v[66:81]
	v_exp_f32_e32 v87, v87
	v_add_f32_e32 v91, v83, v82
	v_exp_f32_e32 v88, v88
	v_add_f32_e32 v91, v84, v91
	v_exp_f32_e32 v89, v89
	v_mfma_f32_32x32x16_bf16 v[66:81], v[228:231], v[126:129], v[66:81]
	v_add_f32_e32 v91, v85, v91
	v_add_f32_e32 v91, v86, v91
	v_add_f32_e32 v91, v87, v91
	v_exp_f32_e32 v167, v92
	v_add_f32_e32 v91, v88, v91
	s_waitcnt lgkmcnt(0)
	v_mfma_f32_32x32x16_bf16 v[66:81], v[232:235], v[130:133], v[66:81]
	v_exp_f32_e32 v93, v93
	v_add_f32_e32 v91, v89, v91
	v_exp_f32_e32 v94, v94
	v_add_f32_e32 v91, v163, v91
	v_mfma_f32_32x32x16_bf16 v[66:81], v[236:239], v[134:137], v[66:81]
	v_exp_f32_e32 v95, v95
	v_add_f32_e32 v91, v166, v91
	v_exp_f32_e32 v96, v96
	v_add_f32_e32 v91, v167, v91
	v_exp_f32_e32 v97, v97
	v_add_f32_e32 v91, v93, v91
	v_mfma_f32_32x32x16_bf16 v[66:81], v[240:243], v[138:141], v[66:81]
	v_add_f32_e32 v91, v94, v91
	v_add_f32_e32 v91, v95, v91
	v_add_f32_e32 v91, v96, v91
	v_add_f32_e32 v91, v97, v91
	v_cvt_pk_bf16_f32 v82, v82, v83
	v_cvt_pk_bf16_f32 v83, v84, v85
	v_mfma_f32_32x32x16_bf16 v[66:81], v[244:247], v[142:145], v[66:81]
	v_mfma_f32_32x32x16_bf16 v[66:81], v[250:253], v[252:255], v[66:81]
	v_cvt_pk_bf16_f32 v84, v86, v87
	v_cvt_pk_bf16_f32 v85, v88, v89
	v_cvt_pk_bf16_f32 v86, v163, v166
	v_cvt_pk_bf16_f32 v87, v167, v93
	v_cvt_pk_bf16_f32 v88, v94, v95
	v_cvt_pk_bf16_f32 v89, v96, v97
	ds_read_b64_tr_b16 v[94:95], v181 offset:0
	ds_read_b64_tr_b16 v[96:97], v181 offset:0x800
	ds_read_b64_tr_b16 v[164:165], v181 offset:0x1000
	ds_read_b64_tr_b16 v[166:167], v181 offset:0x1800
	ds_read_b64_tr_b16 v[168:169], v181 offset:0x200
	ds_read_b64_tr_b16 v[170:171], v181 offset:0xa00
	ds_read_b64_tr_b16 v[204:205], v181 offset:0x1200
	ds_read_b64_tr_b16 v[206:207], v181 offset:0x1a00
	s_nop 0
	v_permlane32_swap_b32_e32 v82, v84
	v_permlane32_swap_b32_e32 v83, v85
	v_permlane32_swap_b32_e32 v86, v88
	v_permlane32_swap_b32_e32 v87, v89
	s_cbranch_scc1 .LBB0_537
	s_and_saveexec_b64 s[66:67], s[0:1]
	ds_write_b32 v196, v249 offset:128
	s_or_b64 exec, exec, s[66:67]
	s_waitcnt lgkmcnt(0)
	v_add_u32_e32 v93, s80, v176
	ds_read_b128 v[232:235], v93 offset:224
	ds_read_b128 v[236:239], v93 offset:192
	ds_read_b128 v[240:243], v93 offset:160
	ds_read_b128 v[244:247], v93 offset:128
	s_waitcnt lgkmcnt(0)
	v_pk_mul_f32 v[62:63], v[62:63], v[232:233]
	v_pk_mul_f32 v[58:59], v[58:59], v[236:237]
	v_pk_mul_f32 v[54:55], v[54:55], v[240:241]
	v_pk_mul_f32 v[64:65], v[64:65], v[234:235]
	v_pk_mul_f32 v[60:61], v[60:61], v[238:239]
	v_pk_mul_f32 v[56:57], v[56:57], v[242:243]
	v_pk_mul_f32 v[52:53], v[52:53], v[246:247]
	v_pk_mul_f32 v[50:51], v[50:51], v[244:245]
	v_pk_mul_f32 v[46:47], v[46:47], v[232:233]
	v_pk_mul_f32 v[42:43], v[42:43], v[236:237]
	v_pk_mul_f32 v[38:39], v[38:39], v[240:241]
	v_pk_mul_f32 v[48:49], v[48:49], v[234:235]
	v_pk_mul_f32 v[44:45], v[44:45], v[238:239]
	v_pk_mul_f32 v[40:41], v[40:41], v[242:243]
	v_pk_mul_f32 v[36:37], v[36:37], v[246:247]
	v_pk_mul_f32 v[34:35], v[34:35], v[244:245]
	v_pk_mul_f32 v[30:31], v[30:31], v[232:233]
	v_pk_mul_f32 v[26:27], v[26:27], v[236:237]
	v_pk_mul_f32 v[22:23], v[22:23], v[240:241]
	v_pk_mul_f32 v[32:33], v[32:33], v[234:235]
	v_pk_mul_f32 v[28:29], v[28:29], v[238:239]
	v_pk_mul_f32 v[24:25], v[24:25], v[242:243]
	v_pk_mul_f32 v[20:21], v[20:21], v[246:247]
	v_pk_mul_f32 v[18:19], v[18:19], v[244:245]
	v_pk_mul_f32 v[14:15], v[14:15], v[232:233]
	v_pk_mul_f32 v[10:11], v[10:11], v[236:237]
	v_pk_mul_f32 v[6:7], v[6:7], v[240:241]
	v_pk_mul_f32 v[16:17], v[16:17], v[234:235]
	v_pk_mul_f32 v[12:13], v[12:13], v[238:239]
	v_pk_mul_f32 v[8:9], v[8:9], v[242:243]
	v_pk_mul_f32 v[4:5], v[4:5], v[246:247]
	v_pk_mul_f32 v[2:3], v[2:3], v[244:245]
.LBB0_537:
.LBB0_539:
	s_nop 1
	s_waitcnt lgkmcnt(4)
	v_mfma_f32_32x32x16_bf16 v[50:65], v[82:85], v[94:97], v[50:65]
	ds_read_b64_tr_b16 v[94:95], v181 offset:0x400
	ds_read_b64_tr_b16 v[96:97], v181 offset:0xc00
	v_max_f32_e32 v93, v66, v67
	ds_read_b64_tr_b16 v[208:209], v181 offset:0x1400
	v_max3_f32 v163, v69, v70, v71
	v_max3_f32 v93, v93, v68, v72
	ds_read_b64_tr_b16 v[210:211], v181 offset:0x1c00
	v_max3_f32 v163, v163, v74, v75
	v_max3_f32 v93, v93, v73, v76
	s_waitcnt lgkmcnt(4)
	v_max3_f32 v163, v163, v78, v79
	v_max3_f32 v93, v93, v77, v80
	ds_read_b64_tr_b16 v[212:213], v181 offset:0x600
	v_max3_f32 v93, v93, v81, v163
	ds_read_b64_tr_b16 v[214:215], v181 offset:0xe00
	v_mov_b32_e32 v163, v93
	ds_read_b64_tr_b16 v[216:217], v181 offset:0x1600
	s_nop 1
	v_permlane32_swap_b32_e32 v93, v163
	ds_read_b64_tr_b16 v[218:219], v181 offset:0x1e00
	s_waitcnt lgkmcnt(4)
	v_max_f32_e32 v93, v93, v163
	v_mfma_f32_32x32x16_bf16 v[18:33], v[82:85], v[94:97], v[18:33]
	v_cmp_ge_f32_e32 vcc, s99, v93
	s_cmp_eq_u64 vcc, exec
	s_cbranch_scc0 .Lrare_11
	v_mov_b32_e32 v93, 1.0
